# phase-1 start offset (~6us) for workgroups with bit3 set, on top of attention/indexer loop rewrites
# baseline (speedup 1.0000x reference)
.LBB0_120:
	v_readlane_b32 s98, v252, 0
	s_nop 0
	s_cmp_lt_u32 s98, 0
	s_cbranch_scc1 .Lstag_skip_p1
	s_lshr_b32 s99, s98, 3
	s_and_b32 s99, s99, 1
	s_mul_i32 s99, s99, 3
	s_cmp_eq_u32 s99, 0
	s_cbranch_scc1 .Lstag_skip_p1
.Lstag_loop_p1:
	s_sleep 64
	s_sub_u32 s99, s99, 1
	s_cmp_lg_u32 s99, 0
	s_cbranch_scc1 .Lstag_loop_p1

	.amdhsa_kernel _Z14fwd_megakernel6Params
		.amdhsa_group_segment_fixed_size 163840
		.amdhsa_private_segment_fixed_size 0
		.amdhsa_kernarg_size 360
		.amdhsa_user_sgpr_count 2
		.amdhsa_user_sgpr_dispatch_ptr 0
		.amdhsa_user_sgpr_queue_ptr 0
		.amdhsa_user_sgpr_kernarg_segment_ptr 1
		.amdhsa_user_sgpr_dispatch_id 0
		.amdhsa_user_sgpr_kernarg_preload_length 0
		.amdhsa_user_sgpr_kernarg_preload_offset 0
		.amdhsa_user_sgpr_private_segment_size 0
		.amdhsa_uses_dynamic_stack 0
		.amdhsa_enable_private_segment 0
		.amdhsa_system_sgpr_workgroup_id_x 1
		.amdhsa_system_sgpr_workgroup_id_y 0
		.amdhsa_system_sgpr_workgroup_id_z 0
		.amdhsa_system_sgpr_workgroup_info 0
		.amdhsa_system_vgpr_workitem_id 2
		.amdhsa_next_free_vgpr 256
		.amdhsa_next_free_sgpr 102
		.amdhsa_accum_offset 256
		.amdhsa_reserve_vcc 1
		.amdhsa_float_round_mode_32 0
		.amdhsa_float_round_mode_16_64 0
		.amdhsa_float_denorm_mode_32 3
		.amdhsa_float_denorm_mode_16_64 3
		.amdhsa_dx10_clamp 1
		.amdhsa_ieee_mode 1
		.amdhsa_fp16_overflow 0
		.amdhsa_tg_split 0
		.amdhsa_exception_fp_ieee_invalid_op 0
		.amdhsa_exception_fp_denorm_src 0
		.amdhsa_exception_fp_ieee_div_zero 0
		.amdhsa_exception_fp_ieee_overflow 0
		.amdhsa_exception_fp_ieee_underflow 0
		.amdhsa_exception_fp_ieee_inexact 0
		.amdhsa_exception_int_div_zero 0
	.end_amdhsa_kernel

amdhsa.kernels:
  - .agpr_count:     0
    .args:
      - .offset:         0
        .size:           104
        .value_kind:     by_value
      - .offset:         104
        .size:           4
        .value_kind:     hidden_block_count_x
      - .offset:         108
        .size:           4
        .value_kind:     hidden_block_count_y
      - .offset:         112
        .size:           4
        .value_kind:     hidden_block_count_z
      - .offset:         116
        .size:           2
        .value_kind:     hidden_group_size_x
      - .offset:         118
        .size:           2
        .value_kind:     hidden_group_size_y
      - .offset:         120
        .size:           2
        .value_kind:     hidden_group_size_z
      - .offset:         122
        .size:           2
        .value_kind:     hidden_remainder_x
      - .offset:         124
        .size:           2
        .value_kind:     hidden_remainder_y
      - .offset:         126
        .size:           2
        .value_kind:     hidden_remainder_z
      - .offset:         144
        .size:           8
        .value_kind:     hidden_global_offset_x
      - .offset:         152
        .size:           8
        .value_kind:     hidden_global_offset_y
      - .offset:         160
        .size:           8
        .value_kind:     hidden_global_offset_z
      - .offset:         168
        .size:           2
        .value_kind:     hidden_grid_dims
      - .offset:         192
        .size:           8
        .value_kind:     hidden_multigrid_sync_arg
    .group_segment_fixed_size: 163840
    .kernarg_segment_align: 8
    .kernarg_segment_size: 360
    .language:       OpenCL C
    .language_version:
      - 2
      - 0
    .max_flat_workgroup_size: 512
    .name:           _Z14fwd_megakernel6Params
    .private_segment_fixed_size: 0
    .sgpr_count:     108
    .sgpr_spill_count: 379
    .symbol:         _Z14fwd_megakernel6Params.kd
    .uniform_work_group_size: 1
    .uses_dynamic_stack: false
    .vgpr_count:     256
    .vgpr_spill_count: 0
    .wavefront_size: 64
